# select phase: 64 sample-row groups spread one per workgroup over 64 workgroups
# baseline (speedup 1.0000x reference)
; __device__ __forceinline__ void sel_params(unsigned char* ws, int l, int tile, int it, int& r0, const bf16_t*& kib, int& n) {
;   if (tile < 256) {
;     const int b = tile >> 5, cp = tile & 31, c = (it & 8) ? 63 - cp : cp;
;     kib = (const bf16_t*)(ws + W_KIP) + (size_t)b * 4096 * 64;
;     r0 = b * 4096 + c * 64 + (it & 7) * 8;
;     n = 64 * (c + 1);
;   } else {
;     const int sb = tile - 256;
;     kib = (const bf16_t*)(ws + W_KIS) + (size_t)(l * 16 + sb) * 2080 * 64;
;     r0 = MP + sb * 32 + it * 8;
;     n = 2080;
;   }
; }
; __device__ __forceinline__ void phase_select(KP kp, int l, unsigned char* shm) {
;     ...
;   for (int tile0 = blockIdx.x; tile0 < 272; tile0 += gridDim.x) {
;     const int tile = tile0 < 256 ? (tile0 & 7) * 32 + (tile0 >> 3) : tile0;
;     const int ng = tile >= 256 ? 4 : 16;
;     SelPre pre;
;     {
;       int r0, n; const bf16_t* kib;
;       sel_params(ws, l, tile, 0, r0, kib, n);
;       sel_prefetch(pre, ws, r0, kib, n, w, lane);
;       sel_prefetch_keys(pre, kib, n, w, lane);
;     }
.LBB0_2882:
	s_or_b64 exec, exec, s[0:1]
	v_readlane_b32 s2, v254, 13
	v_readlane_b32 s0, v254, 2
	v_readlane_b32 s3, v254, 14
	v_readlane_b32 s1, v254, 3
	s_waitcnt lgkmcnt(0)
	v_mov_b32_e32 v0, v244
	s_and_b64 vcc, exec, s[2:3]
	s_barrier
	s_cbranch_vccz .LBB0_3394
	s_load_dwordx2 s[0:1], s[0:1], 0xb0
	v_ashrrev_i32_e32 v198, 6, v0
	v_and_b32_e32 v2, 63, v0
	v_bfe_u32 v196, v0, 5, 1
	v_bfe_u32 v197, v0, 2, 3
	s_waitcnt lgkmcnt(0)
	s_add_u32 s2, s0, 0x1aba2000
	v_writelane_b32 v255, s2, 27
	s_addc_u32 s2, s1, 0
	v_writelane_b32 v255, s2, 29
	s_add_u32 s2, s0, 0xbb80000
	v_writelane_b32 v255, s2, 31
	s_addc_u32 s2, s1, 0
	s_add_u32 s20, s0, 0xab40000
	s_addc_u32 s21, s1, 0
	v_lshlrev_b32_e32 v0, 7, v0
	s_add_u32 s22, s0, 0xc7a0000
	v_and_b32_e32 v16, 0x180, v0
	s_addc_u32 s23, s1, 0
	v_lshl_add_u64 v[0:1], s[20:21], 0, v[16:17]
	v_lshlrev_b32_e32 v16, 4, v196
	s_add_u32 s24, s0, 0x1b3c2000
	v_lshl_add_u64 v[200:201], v[0:1], 0, v[16:17]
	v_lshlrev_b32_e32 v0, 3, v2
	v_ashrrev_i32_e32 v199, 31, v198
	s_addc_u32 s25, s1, 0
	v_readlane_b32 s0, v254, 6
	v_writelane_b32 v255, s2, 33
	v_lshlrev_b64 v[202:203], 12, v[198:199]
	v_add_u32_e32 v199, 8, v198
	v_add_u32_e32 v208, 16, v198
	v_add_u32_e32 v209, 24, v198
	v_lshlrev_b32_e32 v204, 1, v0
	s_mov_b32 s48, s0
	s_lshr_b32 s101, s0, 4
	s_and_b32 s101, s101, 3
	s_and_b32 s100, s0, 15
	s_add_i32 s100, s100, 0x100
	s_cmpk_lt_i32 s0, 0x40
	s_cselect_b32 s100, s100, 0x1000
	v_readlane_b32 s1, v254, 51
	s_cmp_eq_u32 s1, 0
	s_cselect_b32 s100, s100, 0
	s_cselect_b32 s101, s101, 0
	v_readlane_b32 s1, v254, 7
	s_branch .LBB0_2885
.LBB0_2884:
	v_readlane_b32 s0, v254, 0
	s_add_i32 s0, s48, s0
	s_cmpk_lt_i32 s48, 0x100
	s_cselect_b32 s48, s100, 0x1000
	s_cmp_eq_u32 s100, 0
	s_cselect_b32 s48, s0, s48
	s_waitcnt vmcnt(7)
	v_mov_b64_e32 v[18:19], v[164:165]
	s_waitcnt vmcnt(6)
	v_mov_b64_e32 v[22:23], v[168:169]
	s_waitcnt vmcnt(5)
	v_mov_b64_e32 v[26:27], v[172:173]
	s_waitcnt vmcnt(4)
	v_mov_b64_e32 v[30:31], v[176:177]
	s_waitcnt vmcnt(3)
	v_mov_b64_e32 v[34:35], v[180:181]
	s_waitcnt vmcnt(2)
	v_mov_b64_e32 v[38:39], v[184:185]
	s_waitcnt vmcnt(1)
	v_mov_b64_e32 v[42:43], v[188:189]
	s_waitcnt vmcnt(0)
	v_mov_b64_e32 v[46:47], v[192:193]
	s_cmpk_gt_i32 s48, 0x10f
	v_mov_b64_e32 v[20:21], v[166:167]
	v_mov_b64_e32 v[24:25], v[170:171]
	v_mov_b64_e32 v[28:29], v[174:175]
	v_mov_b64_e32 v[32:33], v[178:179]
	v_mov_b64_e32 v[36:37], v[182:183]
	v_mov_b64_e32 v[40:41], v[186:187]
	v_mov_b64_e32 v[44:45], v[190:191]
	v_mov_b64_e32 v[48:49], v[194:195]
	v_readlane_b32 s1, v254, 1
	s_cbranch_scc1 .LBB0_3394
.LBB0_2885:
	s_lshl_b32 s0, s48, 5
	s_and_b32 s0, s0, 0xe0
	s_ashr_i32 s1, s48, 3
	s_add_i32 s0, s0, s1
	s_cmpk_lt_i32 s48, 0x100
	s_cselect_b32 s4, s0, s48
	s_cmpk_gt_i32 s4, 0xff
	s_cselect_b64 s[26:27], -1, 0
	s_mov_b64 s[2:3], -1
	s_and_b64 vcc, exec, s[26:27]
	s_cbranch_vccz .LBB0_2889
	s_add_i32 s2, s4, 0xffffff00
	v_readlane_b32 s0, v255, 24
	s_add_i32 s0, s2, s0
	s_mul_hi_u32 s1, s0, 0x41000
	s_mul_i32 s0, s0, 0x41000
	v_readlane_b32 s3, v255, 27
	s_add_u32 s0, s3, s0
	v_readlane_b32 s3, v255, 29
	s_addc_u32 s1, s3, s1
	s_lshl_b32 s2, s2, 5
	s_add_i32 s6, s2, 0x8000
	s_lshl_b32 s2, s101, 3
	s_add_i32 s6, s6, s2
	s_movk_i32 s5, 0x820
	s_cbranch_execz .LBB0_2890

; __device__ __forceinline__ void phase_select(KP kp, int l, unsigned char* shm) {
;     ...
;     for (int it = 0; it < ng; ++it) {
;       int r0, n, nr0 = 0, nn = 0;
;       const bf16_t *kib, *nkib = nullptr;
;       sel_params(ws, l, tile, it, r0, kib, n);
;       if (it + 1 < ng) sel_params(ws, l, tile, it + 1, nr0, nkib, nn);
.LBB0_2893:
	s_add_i32 s49, s101, 1
	s_cmp_eq_u32 s100, 0
	s_cselect_b32 s49, 4, s49
	s_cmpk_gt_i32 s4, 0xff
	s_cselect_b32 s49, s49, 16
	s_add_i32 s0, s4, 0xffffff00
	v_readlane_b32 s1, v255, 24
	s_add_i32 s1, s0, s1
	s_mul_hi_u32 s2, s1, 0x41000
	s_mul_i32 s1, s1, 0x41000
	v_readlane_b32 s3, v255, 27
	s_add_u32 s28, s3, s1
	v_readlane_b32 s1, v255, 29
	s_addc_u32 s29, s1, s2
	s_lshl_b32 s50, s0, 5
	s_ashr_i32 s0, s4, 5
	s_ashr_i32 s1, s0, 31
	s_add_i32 s50, s50, 0x8000
	s_lshl_b64 s[2:3], s[0:1], 19
	v_readlane_b32 s1, v255, 31
	s_add_u32 s30, s1, s2
	v_readlane_b32 s1, v255, 33
	s_addc_u32 s31, s1, s3
	s_lshl_b32 s51, s0, 12
	s_lshl_b32 s0, s4, 6
	s_and_b32 s52, s0, 0x7c0
	s_waitcnt vmcnt(0)
	v_mov_b64_e32 v[90:91], v[160:161]
	v_mov_b64_e32 v[94:95], v[156:157]
	v_mov_b64_e32 v[98:99], v[152:153]
	v_mov_b64_e32 v[102:103], v[148:149]
	v_mov_b64_e32 v[70:71], v[136:137]
	v_mov_b64_e32 v[74:75], v[132:133]
	s_xor_b32 s53, s52, 0xfc0
	s_cmpk_gt_i32 s4, 0xff
	s_cselect_b32 s54, s101, 0
	v_mov_b64_e32 v[92:93], v[162:163]
	v_mov_b64_e32 v[96:97], v[158:159]
	v_mov_b64_e32 v[100:101], v[154:155]
	v_mov_b64_e32 v[104:105], v[150:151]
	v_mov_b64_e32 v[72:73], v[138:139]
	v_mov_b64_e32 v[76:77], v[134:135]

; __global__ void __launch_bounds__(512, 2) mega(Params p_unused) {
	.amdhsa_kernel _Z4mega6Params
		.amdhsa_group_segment_fixed_size 0
		.amdhsa_private_segment_fixed_size 0
		.amdhsa_kernarg_size 440
		.amdhsa_user_sgpr_count 2
		.amdhsa_user_sgpr_dispatch_ptr 0
		.amdhsa_user_sgpr_queue_ptr 0
		.amdhsa_user_sgpr_kernarg_segment_ptr 1
		.amdhsa_user_sgpr_dispatch_id 0
		.amdhsa_user_sgpr_kernarg_preload_length 0
		.amdhsa_user_sgpr_kernarg_preload_offset 0
		.amdhsa_user_sgpr_private_segment_size 0
		.amdhsa_uses_dynamic_stack 0
		.amdhsa_enable_private_segment 0
		.amdhsa_system_sgpr_workgroup_id_x 1
		.amdhsa_system_sgpr_workgroup_id_y 0
		.amdhsa_system_sgpr_workgroup_id_z 0
		.amdhsa_system_sgpr_workgroup_info 0
		.amdhsa_system_vgpr_workitem_id 2
		.amdhsa_next_free_vgpr 256
		.amdhsa_next_free_sgpr 102
		.amdhsa_accum_offset 256
		.amdhsa_reserve_vcc 1
		.amdhsa_float_round_mode_32 0
		.amdhsa_float_round_mode_16_64 0
		.amdhsa_float_denorm_mode_32 3
		.amdhsa_float_denorm_mode_16_64 3
		.amdhsa_dx10_clamp 1
		.amdhsa_ieee_mode 1
		.amdhsa_fp16_overflow 0
		.amdhsa_tg_split 0
		.amdhsa_exception_fp_ieee_invalid_op 0
		.amdhsa_exception_fp_denorm_src 0
		.amdhsa_exception_fp_ieee_div_zero 0
		.amdhsa_exception_fp_ieee_overflow 0
		.amdhsa_exception_fp_ieee_underflow 0
		.amdhsa_exception_fp_ieee_inexact 0
		.amdhsa_exception_int_div_zero 0
	.end_amdhsa_kernel

; __global__ void __launch_bounds__(512, 2) mega(Params p_unused) {
amdhsa.kernels:
  - .agpr_count:     0
    .args:
      - .offset:         0
        .size:           184
        .value_kind:     by_value
      - .offset:         184
        .size:           4
        .value_kind:     hidden_block_count_x
      - .offset:         188
        .size:           4
        .value_kind:     hidden_block_count_y
      - .offset:         192
        .size:           4
        .value_kind:     hidden_block_count_z
      - .offset:         196
        .size:           2
        .value_kind:     hidden_group_size_x
      - .offset:         198
        .size:           2
        .value_kind:     hidden_group_size_y
      - .offset:         200
        .size:           2
        .value_kind:     hidden_group_size_z
      - .offset:         202
        .size:           2
        .value_kind:     hidden_remainder_x
      - .offset:         204
        .size:           2
        .value_kind:     hidden_remainder_y
      - .offset:         206
        .size:           2
        .value_kind:     hidden_remainder_z
      - .offset:         224
        .size:           8
        .value_kind:     hidden_global_offset_x
      - .offset:         232
        .size:           8
        .value_kind:     hidden_global_offset_y
      - .offset:         240
        .size:           8
        .value_kind:     hidden_global_offset_z
      - .offset:         248
        .size:           2
        .value_kind:     hidden_grid_dims
      - .offset:         272
        .size:           8
        .value_kind:     hidden_multigrid_sync_arg
      - .offset:         304
        .size:           4
        .value_kind:     hidden_dynamic_lds_size
    .group_segment_fixed_size: 0
    .kernarg_segment_align: 8
    .kernarg_segment_size: 440
    .language:       OpenCL C
    .language_version:
      - 2
      - 0
    .max_flat_workgroup_size: 512
    .name:           _Z4mega6Params
    .private_segment_fixed_size: 0
    .sgpr_count:     108
    .sgpr_spill_count: 166
    .symbol:         _Z4mega6Params.kd
    .uniform_work_group_size: 1
    .uses_dynamic_stack: false
    .vgpr_count:     256
    .vgpr_spill_count: 0
    .wavefront_size: 64
